# DA tile loop software-pipelined: k-major P.V first, QK last; cvt of k-steps 1-3 + row-sum + l update of a tile run in the next MFMA block's shadow; first iteration peeled; LDS-DMA issue uses SGPR base
# baseline (speedup 1.0000x reference)
.LBB0_598:
	v_add_f32_e32 v184, v18, v19
	v_lshlrev_b32_e32 v18, 1, v50
	v_and_b32_e32 v18, 32, v18
	v_and_or_b32 v18, v51, s66, v18
	v_and_b32_e32 v19, 0x100, v52
	v_fmac_f32_e32 v184, 0, v56
	v_or3_b32 v187, v18, v19, v53
	s_add_i32 s35, 0, 0xc000
	v_cmp_gt_u32_e64 s[4:5], 32, v50
	v_lshl_add_u32 v186, v54, 2, s18
	v_lshlrev_b32_e32 v185, 4, v55
	v_mov_b64_e32 v[32:33], v[16:17]
	v_mov_b64_e32 v[48:49], v[16:17]
	v_mov_b64_e32 v[64:65], v[16:17]
	s_mov_b32 s96, 1
	v_add_u32_e32 v193, s35, v187
	s_lshl_b32 s97, s12, 8
	s_mov_b32 s12, 0x8000
	s_movk_i32 s74, 0x4000
	s_mov_b32 s0, 0
	v_mov_b64_e32 v[30:31], v[14:15]
	v_mov_b64_e32 v[28:29], v[12:13]
	v_mov_b64_e32 v[26:27], v[10:11]
	v_mov_b64_e32 v[24:25], v[8:9]
	v_mov_b64_e32 v[22:23], v[6:7]
	v_mov_b64_e32 v[20:21], v[4:5]
	v_mov_b64_e32 v[18:19], v[2:3]
	v_mov_b64_e32 v[46:47], v[14:15]
	v_mov_b64_e32 v[44:45], v[12:13]
	v_mov_b64_e32 v[42:43], v[10:11]
	v_mov_b64_e32 v[40:41], v[8:9]
	v_mov_b64_e32 v[38:39], v[6:7]
	v_mov_b64_e32 v[36:37], v[4:5]
	v_mov_b64_e32 v[34:35], v[2:3]
	v_mov_b64_e32 v[62:63], v[14:15]
	v_mov_b64_e32 v[60:61], v[12:13]
	v_mov_b64_e32 v[58:59], v[10:11]
	v_mov_b64_e32 v[56:57], v[8:9]
	v_mov_b64_e32 v[54:55], v[6:7]
	v_mov_b64_e32 v[52:53], v[4:5]
	v_mov_b64_e32 v[50:51], v[2:3]
	s_mov_b32 s75, s74
	s_mov_b32 s74, s0
	v_add_u32_e32 v238, s74, v193
	s_barrier
	s_setprio 3
	ds_read_b128 v[82:85], v188 offset:40960
	ds_read_b128 v[210:213], v188 offset:45056
	ds_read_b128 v[214:217], v189 offset:40960
	ds_read_b128 v[218:221], v189 offset:45056
	ds_read_b128 v[222:225], v190 offset:40960
	ds_read_b128 v[226:229], v190 offset:45056
	ds_read_b128 v[230:233], v191 offset:40960
	ds_read_b128 v[234:237], v191 offset:45056
	ds_read_b64_tr_b16 v[194:195], v238 offset:0
	ds_read_b64_tr_b16 v[196:197], v238 offset:0x800
	ds_read_b64_tr_b16 v[198:199], v238 offset:0x1000
	ds_read_b64_tr_b16 v[200:201], v238 offset:0x1800
	s_waitcnt lgkmcnt(11)
	v_mfma_f32_32x32x16_bf16 v[98:113], v[82:85], v[126:129], v[66:81]
	s_waitcnt lgkmcnt(10)
	v_mfma_f32_32x32x16_bf16 v[82:97], v[210:213], v[126:129], v[66:81]
	ds_read_b64_tr_b16 v[202:203], v238 offset:0x2000
	ds_read_b64_tr_b16 v[204:205], v238 offset:0x2800
	ds_read_b64_tr_b16 v[206:207], v238 offset:0x3000
	ds_read_b64_tr_b16 v[208:209], v238 offset:0x3800
	s_waitcnt lgkmcnt(13)
	v_mfma_f32_32x32x16_bf16 v[98:113], v[214:217], v[122:125], v[98:113]
	s_waitcnt lgkmcnt(12)
	v_mfma_f32_32x32x16_bf16 v[82:97], v[218:221], v[122:125], v[82:97]
	s_waitcnt lgkmcnt(11)
	v_mfma_f32_32x32x16_bf16 v[98:113], v[222:225], v[118:121], v[98:113]
	s_waitcnt lgkmcnt(10)
	v_mfma_f32_32x32x16_bf16 v[82:97], v[226:229], v[118:121], v[82:97]
	s_waitcnt lgkmcnt(9)
	v_mfma_f32_32x32x16_bf16 v[98:113], v[230:233], v[114:117], v[98:113]
	s_waitcnt lgkmcnt(8)
	v_mfma_f32_32x32x16_bf16 v[82:97], v[234:237], v[114:117], v[82:97]
	ds_read_b64_tr_b16 v[210:211], v238 offset:0x200
	ds_read_b64_tr_b16 v[212:213], v238 offset:0xa00
	ds_read_b64_tr_b16 v[214:215], v238 offset:0x1200
	ds_read_b64_tr_b16 v[216:217], v238 offset:0x1a00
	ds_read_b64_tr_b16 v[218:219], v238 offset:0x2200
	ds_read_b64_tr_b16 v[220:221], v238 offset:0x2a00
	ds_read_b64_tr_b16 v[222:223], v238 offset:0x3200
	ds_read_b64_tr_b16 v[224:225], v238 offset:0x3a00
	s_waitcnt lgkmcnt(14)
	v_mfma_f32_32x32x16_bf16 v[50:65], v[142:145], v[194:197], v[50:65]
	s_waitcnt lgkmcnt(12)
	v_mfma_f32_32x32x16_bf16 v[50:65], v[138:141], v[198:201], v[50:65]
	s_waitcnt lgkmcnt(10)
	v_mfma_f32_32x32x16_bf16 v[50:65], v[134:137], v[202:205], v[50:65]
	s_waitcnt lgkmcnt(8)
	v_mfma_f32_32x32x16_bf16 v[50:65], v[130:133], v[206:209], v[50:65]
	ds_read_b64_tr_b16 v[194:195], v238 offset:0x400
	ds_read_b64_tr_b16 v[196:197], v238 offset:0xc00
	ds_read_b64_tr_b16 v[198:199], v238 offset:0x1400
	ds_read_b64_tr_b16 v[200:201], v238 offset:0x1c00
	ds_read_b64_tr_b16 v[202:203], v238 offset:0x2400
	ds_read_b64_tr_b16 v[204:205], v238 offset:0x2c00
	ds_read_b64_tr_b16 v[206:207], v238 offset:0x3400
	ds_read_b64_tr_b16 v[208:209], v238 offset:0x3c00
	s_waitcnt lgkmcnt(14)
	v_mfma_f32_32x32x16_bf16 v[34:49], v[142:145], v[210:213], v[34:49]
	s_waitcnt lgkmcnt(12)
	v_mfma_f32_32x32x16_bf16 v[34:49], v[138:141], v[214:217], v[34:49]
	s_waitcnt lgkmcnt(10)
	v_mfma_f32_32x32x16_bf16 v[34:49], v[134:137], v[218:221], v[34:49]
	s_waitcnt lgkmcnt(8)
	v_mfma_f32_32x32x16_bf16 v[34:49], v[130:133], v[222:225], v[34:49]
	ds_read_b64_tr_b16 v[210:211], v238 offset:0x600
	ds_read_b64_tr_b16 v[212:213], v238 offset:0xe00
	ds_read_b64_tr_b16 v[214:215], v238 offset:0x1600
	ds_read_b64_tr_b16 v[216:217], v238 offset:0x1e00
	ds_read_b64_tr_b16 v[218:219], v238 offset:0x2600
	ds_read_b64_tr_b16 v[220:221], v238 offset:0x2e00
	ds_read_b64_tr_b16 v[222:223], v238 offset:0x3600
	ds_read_b64_tr_b16 v[224:225], v238 offset:0x3e00
	s_waitcnt lgkmcnt(14)
	v_mfma_f32_32x32x16_bf16 v[18:33], v[142:145], v[194:197], v[18:33]
	s_waitcnt lgkmcnt(12)
	v_mfma_f32_32x32x16_bf16 v[18:33], v[138:141], v[198:201], v[18:33]
	s_waitcnt lgkmcnt(10)
	v_mfma_f32_32x32x16_bf16 v[18:33], v[134:137], v[202:205], v[18:33]
	s_waitcnt lgkmcnt(8)
	v_mfma_f32_32x32x16_bf16 v[18:33], v[130:133], v[206:209], v[18:33]
	s_waitcnt lgkmcnt(6)
	v_mfma_f32_32x32x16_bf16 v[2:17], v[142:145], v[210:213], v[2:17]
	s_waitcnt lgkmcnt(4)
	v_mfma_f32_32x32x16_bf16 v[2:17], v[138:141], v[214:217], v[2:17]
	s_waitcnt lgkmcnt(2)
	v_mfma_f32_32x32x16_bf16 v[2:17], v[134:137], v[218:221], v[2:17]
	s_waitcnt lgkmcnt(0)
	v_mfma_f32_32x32x16_bf16 v[2:17], v[130:133], v[222:225], v[2:17]
	s_branch .Lda_after_ma
.LBB0_599:
	s_barrier
	s_setprio 3
	ds_read_b64_tr_b16 v[194:195], v238 offset:0
	ds_read_b64_tr_b16 v[196:197], v238 offset:0x800
	ds_read_b64_tr_b16 v[198:199], v238 offset:0x200
	ds_read_b64_tr_b16 v[200:201], v238 offset:0xa00
	ds_read_b64_tr_b16 v[202:203], v238 offset:0x400
	ds_read_b64_tr_b16 v[204:205], v238 offset:0xc00
	ds_read_b64_tr_b16 v[206:207], v238 offset:0x600
	ds_read_b64_tr_b16 v[208:209], v238 offset:0xe00
	ds_read_b128 v[226:229], v188 offset:45056
	ds_read_b128 v[230:233], v189 offset:40960
	ds_read_b128 v[234:237], v189 offset:45056
	s_waitcnt lgkmcnt(9)
	v_mfma_f32_32x32x16_bf16 v[50:65], v[142:145], v[194:197], v[50:65]
	v_cvt_pk_bf16_f32 v138, v106, v107
	v_add_f32_e32 v242, v98, v99
	v_add_f32_e32 v242, v100, v242
	ds_read_b64_tr_b16 v[210:211], v238 offset:0x1000
	ds_read_b64_tr_b16 v[212:213], v238 offset:0x1800
	s_waitcnt lgkmcnt(9)
	v_mfma_f32_32x32x16_bf16 v[34:49], v[142:145], v[198:201], v[34:49]
	v_cvt_pk_bf16_f32 v139, v108, v109
	v_add_f32_e32 v242, v101, v242
	v_add_f32_e32 v242, v102, v242
	ds_read_b64_tr_b16 v[214:215], v238 offset:0x1200
	ds_read_b64_tr_b16 v[216:217], v238 offset:0x1a00
	s_waitcnt lgkmcnt(9)
	v_mfma_f32_32x32x16_bf16 v[18:33], v[142:145], v[202:205], v[18:33]
	v_cvt_pk_bf16_f32 v140, v110, v111
	v_add_f32_e32 v242, v103, v242
	v_add_f32_e32 v242, v104, v242
	ds_read_b64_tr_b16 v[218:219], v238 offset:0x1400
	ds_read_b64_tr_b16 v[220:221], v238 offset:0x1c00
	s_waitcnt lgkmcnt(9)
	v_mfma_f32_32x32x16_bf16 v[2:17], v[142:145], v[206:209], v[2:17]
	v_cvt_pk_bf16_f32 v141, v112, v113
	v_add_f32_e32 v242, v105, v242
	ds_read_b64_tr_b16 v[222:223], v238 offset:0x1600
	ds_read_b64_tr_b16 v[224:225], v238 offset:0x1e00
	s_waitcnt lgkmcnt(6)
	v_mfma_f32_32x32x16_bf16 v[50:65], v[138:141], v[210:213], v[50:65]
	v_cvt_pk_bf16_f32 v134, v82, v83
	v_add_f32_e32 v242, v106, v242
	v_add_f32_e32 v242, v107, v242
	ds_read_b64_tr_b16 v[194:195], v238 offset:0x2000
	ds_read_b64_tr_b16 v[196:197], v238 offset:0x2800
	s_waitcnt lgkmcnt(6)
	v_mfma_f32_32x32x16_bf16 v[34:49], v[138:141], v[214:217], v[34:49]
	v_cvt_pk_bf16_f32 v135, v84, v85
	v_add_f32_e32 v242, v108, v242
	v_add_f32_e32 v242, v109, v242
	ds_read_b64_tr_b16 v[198:199], v238 offset:0x2200
	ds_read_b64_tr_b16 v[200:201], v238 offset:0x2a00
	s_waitcnt lgkmcnt(6)
	v_mfma_f32_32x32x16_bf16 v[18:33], v[138:141], v[218:221], v[18:33]
	v_cvt_pk_bf16_f32 v136, v86, v87
	v_add_f32_e32 v242, v110, v242
	v_add_f32_e32 v242, v111, v242
	ds_read_b64_tr_b16 v[202:203], v238 offset:0x2400
	ds_read_b64_tr_b16 v[204:205], v238 offset:0x2c00
	s_waitcnt lgkmcnt(6)
	v_mfma_f32_32x32x16_bf16 v[2:17], v[138:141], v[222:225], v[2:17]
	v_cvt_pk_bf16_f32 v137, v88, v89
	v_add_f32_e32 v242, v112, v242
	v_add_f32_e32 v242, v113, v242
	ds_read_b64_tr_b16 v[206:207], v238 offset:0x2600
	ds_read_b64_tr_b16 v[208:209], v238 offset:0x2e00
	s_waitcnt lgkmcnt(6)
	v_mfma_f32_32x32x16_bf16 v[50:65], v[134:137], v[194:197], v[50:65]
	v_cvt_pk_bf16_f32 v130, v90, v91
	v_add_f32_e32 v242, v82, v242
	v_add_f32_e32 v242, v83, v242
	ds_read_b64_tr_b16 v[210:211], v238 offset:0x3000
	ds_read_b64_tr_b16 v[212:213], v238 offset:0x3800
	s_waitcnt lgkmcnt(6)
	v_mfma_f32_32x32x16_bf16 v[34:49], v[134:137], v[198:201], v[34:49]
	v_cvt_pk_bf16_f32 v131, v92, v93
	v_add_f32_e32 v242, v84, v242
	v_add_f32_e32 v242, v85, v242
	ds_read_b64_tr_b16 v[214:215], v238 offset:0x3200
	ds_read_b64_tr_b16 v[216:217], v238 offset:0x3a00
	s_waitcnt lgkmcnt(6)
	v_mfma_f32_32x32x16_bf16 v[18:33], v[134:137], v[202:205], v[18:33]
	v_cvt_pk_bf16_f32 v132, v94, v95
	v_add_f32_e32 v242, v86, v242
	v_add_f32_e32 v242, v87, v242
	ds_read_b64_tr_b16 v[218:219], v238 offset:0x3400
	ds_read_b64_tr_b16 v[220:221], v238 offset:0x3c00
	s_waitcnt lgkmcnt(6)
	v_mfma_f32_32x32x16_bf16 v[2:17], v[134:137], v[206:209], v[2:17]
	v_cvt_pk_bf16_f32 v133, v96, v97
	v_add_f32_e32 v242, v88, v242
	v_add_f32_e32 v242, v89, v242
	ds_read_b64_tr_b16 v[222:223], v238 offset:0x3600
	ds_read_b64_tr_b16 v[224:225], v238 offset:0x3e00
	s_waitcnt lgkmcnt(6)
	v_mfma_f32_32x32x16_bf16 v[50:65], v[130:133], v[210:213], v[50:65]
	v_add_f32_e32 v242, v90, v242
	v_add_f32_e32 v242, v91, v242
	v_add_f32_e32 v242, v92, v242
	v_add_f32_e32 v242, v93, v242
	ds_read_b128 v[82:85], v188 offset:40960
	ds_read_b128 v[194:197], v190 offset:40960
	s_waitcnt lgkmcnt(6)
	v_mfma_f32_32x32x16_bf16 v[34:49], v[130:133], v[214:217], v[34:49]
	v_add_f32_e32 v242, v94, v242
	v_add_f32_e32 v242, v95, v242
	v_add_f32_e32 v242, v96, v242
	v_add_f32_e32 v242, v97, v242
	ds_read_b128 v[198:201], v190 offset:45056
	s_waitcnt lgkmcnt(5)
	v_mfma_f32_32x32x16_bf16 v[18:33], v[130:133], v[218:221], v[18:33]
	v_mov_b32_e32 v243, v242
	s_nop 1
	v_permlane32_swap_b32_e32 v242, v243
	ds_read_b128 v[202:205], v191 offset:40960
	s_waitcnt lgkmcnt(4)
	v_mfma_f32_32x32x16_bf16 v[2:17], v[130:133], v[222:225], v[2:17]
	v_add_f32_e32 v242, v242, v243
	v_fmac_f32_e32 v242, v184, v244
	v_mov_b32_e32 v184, v242
	ds_read_b128 v[206:209], v191 offset:45056
	s_waitcnt lgkmcnt(4)
	v_mfma_f32_32x32x16_bf16 v[98:113], v[82:85], v[126:129], v[66:81]
	v_mfma_f32_32x32x16_bf16 v[82:97], v[226:229], v[126:129], v[66:81]
	v_mfma_f32_32x32x16_bf16 v[98:113], v[230:233], v[122:125], v[98:113]
	v_mfma_f32_32x32x16_bf16 v[82:97], v[234:237], v[122:125], v[82:97]
	s_waitcnt lgkmcnt(3)
	v_mfma_f32_32x32x16_bf16 v[98:113], v[194:197], v[118:121], v[98:113]
	s_waitcnt lgkmcnt(2)
	v_mfma_f32_32x32x16_bf16 v[82:97], v[198:201], v[118:121], v[82:97]
	s_waitcnt lgkmcnt(1)
	v_mfma_f32_32x32x16_bf16 v[98:113], v[202:205], v[114:117], v[98:113]
	s_waitcnt lgkmcnt(0)
	v_mfma_f32_32x32x16_bf16 v[82:97], v[206:209], v[114:117], v[82:97]

.LBB0_601:
	s_and_b64 vcc, exec, s[2:3]
	s_barrier
	s_setprio 0
	s_cbranch_vccnz .LBB0_603
	s_mov_b32 m0, s93
	s_add_i32 s0, s94, s12
	global_load_lds_dwordx4 v150, s[58:59]
	s_add_u32 s58, s58, 0x100000
	s_addc_u32 s59, s59, 0
	s_add_i32 m0, s0, 0xc000
	s_nop 0
	global_load_lds_dwordx4 v170, s[60:61]
	s_add_i32 m0, s0, 0xc400
	s_add_u32 vcc_lo, s60, s24
	s_addc_u32 vcc_hi, s61, s25
	s_add_u32 s60, s60, 0x100000
	s_addc_u32 s61, s61, 0
	s_cmpk_lt_i32 s95, 0x84
	s_cselect_b32 s1, 0, -1
	s_cselect_b32 s0, 0, 0xffd00000
	global_load_lds_dwordx4 v172, vcc
	v_lshl_add_u64 v[130:131], v[174:175], 0, s[0:1]
	s_add_i32 s0, s97, 0
	s_add_i32 m0, s0, 0x18800
	v_lshl_add_u64 v[174:175], v[174:175], 0, s[20:21]
	global_load_lds_dword v[130:131], off
	s_add_i32 s95, s95, 1
.LBB0_603:
	s_and_b64 vcc, exec, s[6:7]
	s_cbranch_vccnz .LBB0_605
	s_add_i32 m0, s92, 0xa000
	s_add_i32 s0, s94, s74
	global_load_lds_dwordx4 v150, s[58:59]
	s_add_u32 s58, s58, 0x100000
	s_addc_u32 s59, s59, 0
	s_add_i32 m0, s0, 0xc000
	s_nop 0
	global_load_lds_dwordx4 v170, s[60:61]
	s_add_i32 m0, s0, 0xc400
	s_add_u32 vcc_lo, s60, s24
	s_addc_u32 vcc_hi, s61, s25
	s_add_u32 s60, s60, 0x100000
	s_addc_u32 s61, s61, 0
	s_cmpk_lt_i32 s95, 0x84
	s_cselect_b32 s1, 0, -1
	s_cselect_b32 s0, 0, 0xffd00000
	global_load_lds_dwordx4 v172, vcc
	v_lshl_add_u64 v[130:131], v[174:175], 0, s[0:1]
	s_add_i32 s0, s97, 0
	s_add_i32 m0, s0, 0x18800
	v_lshl_add_u64 v[174:175], v[174:175], 0, s[20:21]
	global_load_lds_dword v[130:131], off
	s_add_i32 s95, s95, 1

.LBB0_610:
	v_exp_f32_e32 v98, v98
	v_exp_f32_e32 v99, v99
	v_exp_f32_e32 v100, v100
	v_exp_f32_e32 v101, v101
	v_exp_f32_e32 v102, v102
	v_exp_f32_e32 v103, v103
	v_exp_f32_e32 v104, v104
	v_exp_f32_e32 v105, v105
	v_exp_f32_e32 v106, v106
	v_exp_f32_e32 v107, v107
	v_exp_f32_e32 v108, v108
	v_exp_f32_e32 v109, v109
	v_exp_f32_e32 v110, v110
	v_exp_f32_e32 v111, v111
	v_exp_f32_e32 v112, v112
	v_exp_f32_e32 v113, v113
	v_exp_f32_e32 v82, v82
	v_exp_f32_e32 v83, v83
	v_exp_f32_e32 v84, v84
	v_exp_f32_e32 v85, v85
	v_exp_f32_e32 v86, v86
	v_exp_f32_e32 v87, v87
	v_exp_f32_e32 v88, v88
	v_exp_f32_e32 v89, v89
	v_exp_f32_e32 v90, v90
	v_exp_f32_e32 v91, v91
	v_exp_f32_e32 v92, v92
	v_exp_f32_e32 v93, v93
	v_exp_f32_e32 v94, v94
	v_exp_f32_e32 v95, v95
	v_exp_f32_e32 v96, v96
	v_exp_f32_e32 v97, v97
	s_and_b64 vcc, exec, s[2:3]
	v_cvt_pk_bf16_f32 v142, v98, v99
	v_cvt_pk_bf16_f32 v143, v100, v101
	v_cvt_pk_bf16_f32 v144, v102, v103
	v_cvt_pk_bf16_f32 v145, v104, v105
	s_cbranch_vccnz .LBB0_612
	s_waitcnt vmcnt(1)
.LBB0_612:
	s_barrier
	s_setprio 3
	v_add_u32_e32 v197, s75, v193
	ds_read_b64_tr_b16 v[198:199], v197 offset:0
	ds_read_b64_tr_b16 v[200:201], v197 offset:0x800
	ds_read_b64_tr_b16 v[202:203], v197 offset:0x200
	ds_read_b64_tr_b16 v[204:205], v197 offset:0xa00
	ds_read_b64_tr_b16 v[206:207], v197 offset:0x400
	ds_read_b64_tr_b16 v[208:209], v197 offset:0xc00
	ds_read_b64_tr_b16 v[210:211], v197 offset:0x600
	ds_read_b64_tr_b16 v[212:213], v197 offset:0xe00
	ds_read_b128 v[230:233], v188 offset:36864
	ds_read_b128 v[234:237], v189 offset:32768
	ds_read_b128 v[238:241], v189 offset:36864
	s_waitcnt lgkmcnt(9)
	v_mfma_f32_32x32x16_bf16 v[50:65], v[142:145], v[198:201], v[50:65]
	v_cvt_pk_bf16_f32 v138, v106, v107
	v_add_f32_e32 v242, v98, v99
	v_add_f32_e32 v242, v100, v242
	ds_read_b64_tr_b16 v[214:215], v197 offset:0x1000
	ds_read_b64_tr_b16 v[216:217], v197 offset:0x1800
	s_waitcnt lgkmcnt(9)
	v_mfma_f32_32x32x16_bf16 v[34:49], v[142:145], v[202:205], v[34:49]
	v_cvt_pk_bf16_f32 v139, v108, v109
	v_add_f32_e32 v242, v101, v242
	v_add_f32_e32 v242, v102, v242
	ds_read_b64_tr_b16 v[218:219], v197 offset:0x1200
	ds_read_b64_tr_b16 v[220:221], v197 offset:0x1a00
	s_waitcnt lgkmcnt(9)
	v_mfma_f32_32x32x16_bf16 v[18:33], v[142:145], v[206:209], v[18:33]
	v_cvt_pk_bf16_f32 v140, v110, v111
	v_add_f32_e32 v242, v103, v242
	v_add_f32_e32 v242, v104, v242
	ds_read_b64_tr_b16 v[222:223], v197 offset:0x1400
	ds_read_b64_tr_b16 v[224:225], v197 offset:0x1c00
	s_waitcnt lgkmcnt(9)
	v_mfma_f32_32x32x16_bf16 v[2:17], v[142:145], v[210:213], v[2:17]
	v_cvt_pk_bf16_f32 v141, v112, v113
	v_add_f32_e32 v242, v105, v242
	ds_read_b64_tr_b16 v[226:227], v197 offset:0x1600
	ds_read_b64_tr_b16 v[228:229], v197 offset:0x1e00
	s_waitcnt lgkmcnt(6)
	v_mfma_f32_32x32x16_bf16 v[50:65], v[138:141], v[214:217], v[50:65]
	v_cvt_pk_bf16_f32 v134, v82, v83
	v_add_f32_e32 v242, v106, v242
	v_add_f32_e32 v242, v107, v242
	ds_read_b64_tr_b16 v[198:199], v197 offset:0x2000
	ds_read_b64_tr_b16 v[200:201], v197 offset:0x2800
	s_waitcnt lgkmcnt(6)
	v_mfma_f32_32x32x16_bf16 v[34:49], v[138:141], v[218:221], v[34:49]
	v_cvt_pk_bf16_f32 v135, v84, v85
	v_add_f32_e32 v242, v108, v242
	v_add_f32_e32 v242, v109, v242
	ds_read_b64_tr_b16 v[202:203], v197 offset:0x2200
	ds_read_b64_tr_b16 v[204:205], v197 offset:0x2a00
	s_waitcnt lgkmcnt(6)
	v_mfma_f32_32x32x16_bf16 v[18:33], v[138:141], v[222:225], v[18:33]
	v_cvt_pk_bf16_f32 v136, v86, v87
	v_add_f32_e32 v242, v110, v242
	v_add_f32_e32 v242, v111, v242
	ds_read_b64_tr_b16 v[206:207], v197 offset:0x2400
	ds_read_b64_tr_b16 v[208:209], v197 offset:0x2c00
	s_waitcnt lgkmcnt(6)
	v_mfma_f32_32x32x16_bf16 v[2:17], v[138:141], v[226:229], v[2:17]
	v_cvt_pk_bf16_f32 v137, v88, v89
	v_add_f32_e32 v242, v112, v242
	v_add_f32_e32 v242, v113, v242
	ds_read_b64_tr_b16 v[210:211], v197 offset:0x2600
	ds_read_b64_tr_b16 v[212:213], v197 offset:0x2e00
	s_waitcnt lgkmcnt(6)
	v_mfma_f32_32x32x16_bf16 v[50:65], v[134:137], v[198:201], v[50:65]
	v_cvt_pk_bf16_f32 v130, v90, v91
	v_add_f32_e32 v242, v82, v242
	v_add_f32_e32 v242, v83, v242
	ds_read_b64_tr_b16 v[214:215], v197 offset:0x3000
	ds_read_b64_tr_b16 v[216:217], v197 offset:0x3800
	s_waitcnt lgkmcnt(6)
	v_mfma_f32_32x32x16_bf16 v[34:49], v[134:137], v[202:205], v[34:49]
	v_cvt_pk_bf16_f32 v131, v92, v93
	v_add_f32_e32 v242, v84, v242
	v_add_f32_e32 v242, v85, v242
	ds_read_b64_tr_b16 v[218:219], v197 offset:0x3200
	ds_read_b64_tr_b16 v[220:221], v197 offset:0x3a00
	s_waitcnt lgkmcnt(6)
	v_mfma_f32_32x32x16_bf16 v[18:33], v[134:137], v[206:209], v[18:33]
	v_cvt_pk_bf16_f32 v132, v94, v95
	v_add_f32_e32 v242, v86, v242
	v_add_f32_e32 v242, v87, v242
	ds_read_b64_tr_b16 v[222:223], v197 offset:0x3400
	ds_read_b64_tr_b16 v[224:225], v197 offset:0x3c00
	s_waitcnt lgkmcnt(6)
	v_mfma_f32_32x32x16_bf16 v[2:17], v[134:137], v[210:213], v[2:17]
	v_cvt_pk_bf16_f32 v133, v96, v97
	v_add_f32_e32 v242, v88, v242
	v_add_f32_e32 v242, v89, v242
	ds_read_b64_tr_b16 v[226:227], v197 offset:0x3600
	ds_read_b64_tr_b16 v[228:229], v197 offset:0x3e00
	s_waitcnt lgkmcnt(6)
	v_mfma_f32_32x32x16_bf16 v[50:65], v[130:133], v[214:217], v[50:65]
	v_add_f32_e32 v242, v90, v242
	v_add_f32_e32 v242, v91, v242
	v_add_f32_e32 v242, v92, v242
	v_add_f32_e32 v242, v93, v242
	ds_read_b128 v[82:85], v188 offset:32768
	ds_read_b128 v[198:201], v190 offset:32768
	s_waitcnt lgkmcnt(6)
	v_mfma_f32_32x32x16_bf16 v[34:49], v[130:133], v[218:221], v[34:49]
	v_add_f32_e32 v242, v94, v242
	v_add_f32_e32 v242, v95, v242
	v_add_f32_e32 v242, v96, v242
	v_add_f32_e32 v242, v97, v242
	ds_read_b128 v[202:205], v190 offset:36864
	s_waitcnt lgkmcnt(5)
	v_mfma_f32_32x32x16_bf16 v[18:33], v[130:133], v[222:225], v[18:33]
	v_mov_b32_e32 v243, v242
	s_nop 1
	v_permlane32_swap_b32_e32 v242, v243
	ds_read_b128 v[206:209], v191 offset:32768
	s_waitcnt lgkmcnt(4)
	v_mfma_f32_32x32x16_bf16 v[2:17], v[130:133], v[226:229], v[2:17]
	v_add_f32_e32 v242, v242, v243
	v_fmac_f32_e32 v242, v184, v194
	v_mov_b32_e32 v184, v242
	ds_read_b128 v[210:213], v191 offset:36864
	s_waitcnt lgkmcnt(4)
	v_mfma_f32_32x32x16_bf16 v[98:113], v[82:85], v[126:129], v[66:81]
	v_mfma_f32_32x32x16_bf16 v[82:97], v[230:233], v[126:129], v[66:81]
	v_mfma_f32_32x32x16_bf16 v[98:113], v[234:237], v[122:125], v[98:113]
	v_mfma_f32_32x32x16_bf16 v[82:97], v[238:241], v[122:125], v[82:97]
	s_waitcnt lgkmcnt(3)
	v_mfma_f32_32x32x16_bf16 v[98:113], v[198:201], v[118:121], v[98:113]
	s_waitcnt lgkmcnt(2)
	v_mfma_f32_32x32x16_bf16 v[82:97], v[202:205], v[118:121], v[82:97]
	s_waitcnt lgkmcnt(1)
	v_mfma_f32_32x32x16_bf16 v[98:113], v[206:209], v[114:117], v[98:113]
	s_waitcnt lgkmcnt(0)
	v_mfma_f32_32x32x16_bf16 v[82:97], v[210:213], v[114:117], v[82:97]
	s_and_b64 vcc, exec, s[6:7]
	s_cbranch_vccnz .LBB0_614
	s_waitcnt vmcnt(1)
.LBB0_614:
	s_and_b64 vcc, exec, s[2:3]
	s_barrier
	s_setprio 0
	s_cbranch_vccnz .LBB0_616
	s_add_i32 m0, s92, 0xa000
	s_add_i32 s0, s94, s74
	global_load_lds_dwordx4 v150, s[58:59]
	s_add_u32 s58, s58, 0x100000
	s_addc_u32 s59, s59, 0
	s_add_i32 m0, s0, 0xc000
	s_nop 0
	global_load_lds_dwordx4 v170, s[60:61]
	s_add_i32 m0, s0, 0xc400
	s_add_u32 vcc_lo, s60, s24
	s_addc_u32 vcc_hi, s61, s25
	s_add_u32 s60, s60, 0x100000
	s_addc_u32 s61, s61, 0
	s_cmpk_lt_i32 s95, 0x84
	s_cselect_b32 s1, 0, -1
	s_cselect_b32 s0, 0, 0xffd00000
	global_load_lds_dwordx4 v172, vcc
	v_lshl_add_u64 v[130:131], v[174:175], 0, s[0:1]
	s_add_i32 s0, s97, 0
	s_add_i32 m0, s0, 0x18800
	v_lshl_add_u64 v[174:175], v[174:175], 0, s[20:21]
	global_load_lds_dword v[130:131], off
	s_add_i32 s95, s95, 1
.LBB0_616:
	s_cmpk_gt_u32 s96, 0x80
	s_cselect_b64 s[0:1], -1, 0
	s_cmpk_lt_u32 s96, 0x81
	s_cselect_b64 s[62:63], -1, 0
	s_and_b64 s[62:63], s[56:57], s[62:63]
	s_andn2_b64 vcc, exec, s[62:63]
	s_cbranch_vccnz .LBB0_618
	s_mov_b32 m0, s93
	s_add_i32 s13, s94, s75
	global_load_lds_dwordx4 v150, s[58:59]
	s_add_u32 s58, s58, 0x100000
	s_addc_u32 s59, s59, 0
	s_add_i32 m0, s13, 0xc000
	s_nop 0
	global_load_lds_dwordx4 v170, s[60:61]
	s_add_i32 m0, s13, 0xc400
	s_add_u32 vcc_lo, s60, s24
	s_addc_u32 vcc_hi, s61, s25
	s_add_u32 s60, s60, 0x100000
	s_addc_u32 s61, s61, 0
	s_cmpk_lt_i32 s95, 0x84
	s_cselect_b32 s63, 0, -1
	s_cselect_b32 s62, 0, 0xffd00000
	s_add_i32 s13, s97, 0
	global_load_lds_dwordx4 v172, vcc
	v_lshl_add_u64 v[130:131], v[174:175], 0, s[62:63]
	s_add_i32 m0, s13, 0x18800
	v_lshl_add_u64 v[174:175], v[174:175], 0, s[20:21]
	global_load_lds_dword v[130:131], off
	s_add_i32 s95, s95, 1

.Lrot_da_exit:
	s_barrier
	v_cvt_pk_bf16_f32 v138, v106, v107
	v_cvt_pk_bf16_f32 v139, v108, v109
	v_cvt_pk_bf16_f32 v140, v110, v111
	v_cvt_pk_bf16_f32 v141, v112, v113
	v_cvt_pk_bf16_f32 v134, v82, v83
	v_cvt_pk_bf16_f32 v135, v84, v85
	v_cvt_pk_bf16_f32 v136, v86, v87
	v_cvt_pk_bf16_f32 v137, v88, v89
	v_cvt_pk_bf16_f32 v130, v90, v91
	v_cvt_pk_bf16_f32 v131, v92, v93
	v_cvt_pk_bf16_f32 v132, v94, v95
	v_cvt_pk_bf16_f32 v133, v96, v97
	v_add_f32_e32 v242, v98, v99
	v_add_f32_e32 v242, v100, v242
	v_add_f32_e32 v242, v101, v242
	v_add_f32_e32 v242, v102, v242
	v_add_f32_e32 v242, v103, v242
	v_add_f32_e32 v242, v104, v242
	v_add_f32_e32 v242, v105, v242
	v_add_f32_e32 v242, v106, v242
	v_add_f32_e32 v242, v107, v242
	v_add_f32_e32 v242, v108, v242
	v_add_f32_e32 v242, v109, v242
	v_add_f32_e32 v242, v110, v242
	v_add_f32_e32 v242, v111, v242
	v_add_f32_e32 v242, v112, v242
	v_add_f32_e32 v242, v113, v242
	v_add_f32_e32 v242, v82, v242
	v_add_f32_e32 v242, v83, v242
	v_add_f32_e32 v242, v84, v242
	v_add_f32_e32 v242, v85, v242
	v_add_f32_e32 v242, v86, v242
	v_add_f32_e32 v242, v87, v242
	v_add_f32_e32 v242, v88, v242
	v_add_f32_e32 v242, v89, v242
	v_add_f32_e32 v242, v90, v242
	v_add_f32_e32 v242, v91, v242
	v_add_f32_e32 v242, v92, v242
	v_add_f32_e32 v242, v93, v242
	v_add_f32_e32 v242, v94, v242
	v_add_f32_e32 v242, v95, v242
	v_add_f32_e32 v242, v96, v242
	v_add_f32_e32 v242, v97, v242
	v_mov_b32_e32 v243, v242
	s_nop 1
	v_permlane32_swap_b32_e32 v242, v243
	v_add_f32_e32 v242, v242, v243
	v_fmac_f32_e32 v242, v184, v244
	v_mov_b32_e32 v184, v242
	s_branch .LBB0_629
